# weight-conversion loads de-serialized: the 8 (+8 scale) loads of each 64x64 job issued back to back with one wait (was load/wait per element row)
# speedup vs baseline: 1.0497x; 1.0319x over previous
; __device__ __forceinline__ void prep_load(const KP& p, int job, int tid, float (&v)[8], PrepMeta& m) {
;     ...
;   for (int it = 0; it < 8; ++it) {
;     int e = tid + 512 * it, kk = e >> 6, nn = e & 63;
;     int k = k0 + kk, n = n0 + nn, c; bool ok = true; const float* sp = s0;
;     const int nl = n & 255, bj = nl >> 7, wc_ = (nl >> 5) & 3, ns = (nl >> 4) & 1, r = nl & 15;
;     if (mat == 0) { c = (n >> 8) * 128 + wc_ * 32 + (r >> 2) * 8 + bj * 4 + (r & 3); if (ns) sp = s1; }
;     else {
;       c = (n & ~255) + bj * 128 + wc_ * 32 + (r >> 2) * 8 + ns * 4 + (r & 3);
;       if (mat == 2) { if (c < 1536) c = c; else if (c < 3584) c = c + 8; else if (c < 3592) c = 1536 + (c - 3584); else { ok = false; c = 0; } }
;     }
;     float x = sp[(size_t)k * ldn + c] * cs;
;     if (sc) x *= sc[k];
;     v[it] = ok ? x : 0.f;
;   }
.LBB0_56:
	s_lshl_b32 s77, s3, 6
	s_lshl_b32 s76, s40, 6
	s_bfe_u32 s15, s3, 0x10001
	v_and_or_b32 v0, v37, 32, s77
	s_cmp_lg_u64 s[36:37], 0
	v_bfe_u32 v0, v0, 5, 2
	s_cselect_b64 s[80:81], -1, 0
	s_and_b32 s0, s77, 0xffffff00
	s_lshl_b32 s1, s15, 7
	v_lshlrev_b32_e32 v4, 1, v37
	v_bfe_u32 v2, v37, 4, 1
	s_or_b32 s0, s1, s0
	v_lshlrev_b32_e32 v3, 5, v0
	v_and_b32_e32 v4, 24, v4
	v_or3_b32 v3, v3, s0, v4
	v_lshlrev_b32_e32 v5, 2, v2
	v_and_b32_e32 v6, 3, v37
	v_or3_b32 v5, v5, v6, v3
	s_movk_i32 s0, 0x600
	s_cmpk_lt_u32 s77, 0xe00
	v_cmp_gt_i32_e32 vcc, s0, v5
	s_cselect_b64 s[0:1], -1, 0
	s_and_b32 s3, s3, 0x7fffffc
	s_lshl_b32 s15, s15, 2
	v_or_b32_e32 v0, s3, v0
	s_or_b64 s[38:39], s[74:75], s[38:39]
	v_lshl_or_b32 v0, v0, 5, s15
	s_or_b64 s[38:39], s[38:39], vcc
	v_or3_b32 v0, v0, v4, v6
	v_cmp_eq_u32_e32 vcc, 0, v2
	v_mov_b32_e32 v2, s78
	v_mov_b32_e32 v4, s42
	s_movk_i32 s40, 0xe08
	v_cndmask_b32_e32 v8, v2, v4, vcc
	v_mov_b32_e32 v2, s79
	v_mov_b32_e32 v9, s43
	v_cmp_gt_u32_e64 s[40:41], s40, v3
	v_add_u32_e32 v3, 0xfffff800, v5
	v_cndmask_b32_e32 v10, v2, v9, vcc
	v_ashrrev_i32_e32 v2, 6, v37
	v_cndmask_b32_e64 v3, 0, v3, s[40:41]
	v_add_u32_e32 v7, 8, v5
	v_add_u32_e32 v6, s76, v2
	v_cndmask_b32_e64 v0, v5, v0, s[74:75]
	v_cndmask_b32_e64 v2, v3, v7, s[0:1]
	v_ashrrev_i32_e32 v7, 31, v6
	v_cndmask_b32_e64 v2, v2, v0, s[38:39]
	v_cndmask_b32_e64 v5, v9, v10, s[74:75]
	v_cndmask_b32_e64 v4, v4, v8, s[74:75]
	v_mul_lo_u32 v0, s50, v7
	v_mul_lo_u32 v3, s51, v6
	v_mad_u64_u32 v[8:9], s[42:43], s50, v6, 0
	v_add3_u32 v9, v9, v0, v3
	v_ashrrev_i32_e32 v3, 31, v2
	v_lshl_add_u64 v[8:9], v[8:9], 2, v[4:5]
	v_lshl_add_u64 v[8:9], v[2:3], 2, v[8:9]
	v_mov_b32_e32 v60, 1.0
	v_mov_b32_e32 v61, 1.0
	v_mov_b32_e32 v62, 1.0
	v_mov_b32_e32 v63, 1.0
	v_mov_b32_e32 v64, 1.0
	v_mov_b32_e32 v65, 1.0
	v_mov_b32_e32 v66, 1.0
	v_mov_b32_e32 v67, 1.0
	global_load_dword v0, v[8:9], off
	s_cmp_eq_u64 s[36:37], 0
	s_cbranch_scc1 .LBB0_58
	v_lshl_add_u64 v[6:7], v[6:7], 2, s[36:37]
	global_load_dword v60, v[6:7], off
.LBB0_58:
	v_add_u32_e32 v6, 0x200, v37
	v_ashrrev_i32_e32 v6, 6, v6
	v_add_u32_e32 v6, s76, v6
	v_ashrrev_i32_e32 v7, 31, v6
	v_mul_lo_u32 v10, s50, v7
	v_mul_lo_u32 v11, s51, v6
	v_mad_u64_u32 v[8:9], s[42:43], s50, v6, 0
	v_add3_u32 v9, v9, v10, v11
	v_lshl_add_u64 v[8:9], v[8:9], 2, v[4:5]
	v_lshl_add_u64 v[8:9], v[2:3], 2, v[8:9]
	global_load_dword v8, v[8:9], off
	v_cndmask_b32_e64 v9, 0, 1, s[80:81]
	v_cmp_ne_u32_e64 s[42:43], 1, v9
	s_andn2_b64 vcc, exec, s[80:81]
	s_cbranch_vccnz .LBB0_60
	v_lshl_add_u64 v[6:7], v[6:7], 2, s[36:37]
	global_load_dword v61, v[6:7], off
.LBB0_60:
	v_add_u32_e32 v6, 0x400, v37
	v_ashrrev_i32_e32 v6, 6, v6
	v_add_u32_e32 v6, s76, v6
	v_ashrrev_i32_e32 v7, 31, v6
	v_mul_lo_u32 v9, s50, v7
	v_mul_lo_u32 v12, s51, v6
	v_mad_u64_u32 v[10:11], s[56:57], s50, v6, 0
	v_add3_u32 v11, v11, v9, v12
	v_lshl_add_u64 v[10:11], v[10:11], 2, v[4:5]
	v_lshl_add_u64 v[10:11], v[2:3], 2, v[10:11]
	global_load_dword v9, v[10:11], off
	s_and_b64 vcc, exec, s[42:43]
	s_cbranch_vccnz .LBB0_62
	v_lshl_add_u64 v[6:7], v[6:7], 2, s[36:37]
	global_load_dword v62, v[6:7], off
.LBB0_62:
	v_add_u32_e32 v6, 0x600, v37
	v_ashrrev_i32_e32 v6, 6, v6
	v_add_u32_e32 v6, s76, v6
	v_ashrrev_i32_e32 v7, 31, v6
	v_mul_lo_u32 v12, s50, v7
	v_mul_lo_u32 v13, s51, v6
	v_mad_u64_u32 v[10:11], s[56:57], s50, v6, 0
	v_add3_u32 v11, v11, v12, v13
	v_lshl_add_u64 v[10:11], v[10:11], 2, v[4:5]
	v_lshl_add_u64 v[10:11], v[2:3], 2, v[10:11]
	global_load_dword v10, v[10:11], off
	s_and_b64 vcc, exec, s[42:43]
	s_cbranch_vccnz .LBB0_64
	v_lshl_add_u64 v[6:7], v[6:7], 2, s[36:37]
	global_load_dword v63, v[6:7], off
.LBB0_64:
	v_add_u32_e32 v6, 0x800, v37
	v_ashrrev_i32_e32 v6, 6, v6
	v_add_u32_e32 v6, s76, v6
	v_ashrrev_i32_e32 v7, 31, v6
	v_mul_lo_u32 v11, s50, v7
	v_mul_lo_u32 v14, s51, v6
	v_mad_u64_u32 v[12:13], s[56:57], s50, v6, 0
	v_add3_u32 v13, v13, v11, v14
	v_lshl_add_u64 v[12:13], v[12:13], 2, v[4:5]
	v_lshl_add_u64 v[12:13], v[2:3], 2, v[12:13]
	global_load_dword v11, v[12:13], off
	s_and_b64 vcc, exec, s[42:43]
	s_cbranch_vccnz .LBB0_66
	v_lshl_add_u64 v[6:7], v[6:7], 2, s[36:37]
	global_load_dword v64, v[6:7], off
.LBB0_66:
	v_add_u32_e32 v6, 0xa00, v37
	v_ashrrev_i32_e32 v6, 6, v6
	v_add_u32_e32 v6, s76, v6
	v_ashrrev_i32_e32 v7, 31, v6
	v_mul_lo_u32 v14, s50, v7
	v_mul_lo_u32 v15, s51, v6
	v_mad_u64_u32 v[12:13], s[56:57], s50, v6, 0
	v_add3_u32 v13, v13, v14, v15
	v_lshl_add_u64 v[12:13], v[12:13], 2, v[4:5]
	v_lshl_add_u64 v[12:13], v[2:3], 2, v[12:13]
	global_load_dword v12, v[12:13], off
	s_and_b64 vcc, exec, s[42:43]
	s_cbranch_vccnz .LBB0_68
	v_lshl_add_u64 v[6:7], v[6:7], 2, s[36:37]
	global_load_dword v65, v[6:7], off
.LBB0_68:
	v_add_u32_e32 v6, 0xc00, v37
	v_ashrrev_i32_e32 v6, 6, v6
	v_add_u32_e32 v6, s76, v6
	v_ashrrev_i32_e32 v7, 31, v6
	v_mul_lo_u32 v13, s50, v7
	v_mul_lo_u32 v16, s51, v6
	v_mad_u64_u32 v[14:15], s[56:57], s50, v6, 0
	v_add3_u32 v15, v15, v13, v16
	v_lshl_add_u64 v[14:15], v[14:15], 2, v[4:5]
	v_lshl_add_u64 v[14:15], v[2:3], 2, v[14:15]
	global_load_dword v13, v[14:15], off
	s_and_b64 vcc, exec, s[42:43]
	s_cbranch_vccnz .LBB0_70
	v_lshl_add_u64 v[6:7], v[6:7], 2, s[36:37]
	global_load_dword v66, v[6:7], off
.LBB0_70:
	v_add_u32_e32 v6, 0xe00, v37
	v_ashrrev_i32_e32 v6, 6, v6
	v_add_u32_e32 v6, s76, v6
	v_ashrrev_i32_e32 v7, 31, v6
	v_mul_lo_u32 v16, s50, v7
	v_mul_lo_u32 v17, s51, v6
	v_mad_u64_u32 v[14:15], s[50:51], s50, v6, 0
	v_add3_u32 v15, v15, v16, v17
	v_lshl_add_u64 v[4:5], v[14:15], 2, v[4:5]
	v_lshl_add_u64 v[2:3], v[2:3], 2, v[4:5]
	global_load_dword v75, v[2:3], off
	s_and_b64 vcc, exec, s[42:43]
	s_cbranch_vccnz .LBB0_72
	v_lshl_add_u64 v[2:3], v[6:7], 2, s[36:37]
	global_load_dword v67, v[2:3], off
.LBB0_72:
	s_waitcnt vmcnt(0)
	v_mul_f32_e32 v0, s2, v0
	v_mul_f32_e32 v8, s2, v8
	v_mul_f32_e32 v9, s2, v9
	v_mul_f32_e32 v10, s2, v10
	v_mul_f32_e32 v11, s2, v11
	v_mul_f32_e32 v12, s2, v12
	v_mul_f32_e32 v13, s2, v13
	v_mul_f32_e32 v14, s2, v75
	v_mul_f32_e32 v0, v0, v60
	v_mul_f32_e32 v8, v8, v61
	v_mul_f32_e32 v9, v9, v62
	v_mul_f32_e32 v10, v10, v63
	v_mul_f32_e32 v11, v11, v64
	v_mul_f32_e32 v12, v12, v65
	v_mul_f32_e32 v13, v13, v66
	v_mul_f32_e32 v14, v14, v67
	s_or_b64 s[0:1], s[38:39], s[0:1]
	s_or_b64 vcc, s[0:1], s[40:41]
	v_cndmask_b32_e32 v2, 0, v0, vcc
	v_cndmask_b32_e32 v3, 0, v8, vcc
	v_cndmask_b32_e32 v4, 0, v9, vcc
	v_cndmask_b32_e32 v5, 0, v10, vcc
	v_cndmask_b32_e32 v6, 0, v11, vcc
	v_cndmask_b32_e32 v7, 0, v12, vcc
	v_cndmask_b32_e32 v8, 0, v13, vcc
	v_cndmask_b32_e32 v9, 0, v14, vcc
	s_branch .LBB0_74

; __device__ __forceinline__ void prep_load(const KP& p, int job, int tid, float (&v)[8], PrepMeta& m) {
;     ...
;   for (int it = 0; it < 8; ++it) {
;     int e = tid + 512 * it, kk = e >> 6, nn = e & 63;
;     int k = k0 + kk, n = n0 + nn, c; bool ok = true; const float* sp = s0;
;     const int nl = n & 255, bj = nl >> 7, wc_ = (nl >> 5) & 3, ns = (nl >> 4) & 1, r = nl & 15;
;     if (mat == 0) { c = (n >> 8) * 128 + wc_ * 32 + (r >> 2) * 8 + bj * 4 + (r & 3); if (ns) sp = s1; }
;     else {
;       c = (n & ~255) + bj * 128 + wc_ * 32 + (r >> 2) * 8 + ns * 4 + (r & 3);
;       if (mat == 2) { if (c < 1536) c = c; else if (c < 3584) c = c + 8; else if (c < 3592) c = 1536 + (c - 3584); else { ok = false; c = 0; } }
;     }
;     float x = sp[(size_t)k * ldn + c] * cs;
;     if (sc) x *= sc[k];
;     v[it] = ok ? x : 0.f;
;   }
.LBB0_94:
	s_lshl_b32 s37, s3, 6
	s_lshl_b32 s74, s41, 6
	s_bfe_u32 s40, s3, 0x10001
	v_and_or_b32 v0, v37, 32, s37
	s_cmp_lg_u64 s[78:79], 0
	v_bfe_u32 v0, v0, 5, 2
	s_cselect_b64 s[86:87], -1, 0
	s_and_b32 s0, s37, 0xffffff00
	s_lshl_b32 s1, s40, 7
	v_lshlrev_b32_e32 v12, 1, v37
	v_bfe_u32 v10, v37, 4, 1
	s_or_b32 s0, s1, s0
	v_lshlrev_b32_e32 v11, 5, v0
	v_and_b32_e32 v12, 24, v12
	v_or3_b32 v11, v11, s0, v12
	v_lshlrev_b32_e32 v13, 2, v10
	v_and_b32_e32 v14, 3, v37
	v_or3_b32 v13, v13, v14, v11
	s_movk_i32 s0, 0x600
	s_cmpk_lt_u32 s37, 0xe00
	v_cmp_gt_i32_e32 vcc, s0, v13
	s_cselect_b64 s[0:1], -1, 0
	s_and_b32 s3, s3, 0x7fffffc
	s_lshl_b32 s56, s40, 2
	v_or_b32_e32 v0, s3, v0
	s_or_b64 s[38:39], s[82:83], s[38:39]
	v_lshl_or_b32 v0, v0, 5, s56
	s_or_b64 s[38:39], s[38:39], vcc
	v_or3_b32 v0, v0, v12, v14
	v_cmp_eq_u32_e32 vcc, 0, v10
	v_mov_b32_e32 v10, s84
	v_mov_b32_e32 v12, s42
	s_movk_i32 s40, 0xe08
	v_cndmask_b32_e32 v16, v10, v12, vcc
	v_mov_b32_e32 v10, s85
	v_mov_b32_e32 v17, s43
	v_cmp_gt_u32_e64 s[40:41], s40, v11
	v_add_u32_e32 v11, 0xfffff800, v13
	v_cndmask_b32_e32 v18, v10, v17, vcc
	v_ashrrev_i32_e32 v10, 6, v37
	v_cndmask_b32_e64 v11, 0, v11, s[40:41]
	v_add_u32_e32 v15, 8, v13
	v_add_u32_e32 v14, s74, v10
	v_cndmask_b32_e64 v0, v13, v0, s[82:83]
	v_cndmask_b32_e64 v10, v11, v15, s[0:1]
	v_ashrrev_i32_e32 v15, 31, v14
	v_cndmask_b32_e64 v10, v10, v0, s[38:39]
	v_cndmask_b32_e64 v13, v17, v18, s[82:83]
	v_cndmask_b32_e64 v12, v12, v16, s[82:83]
	v_mul_lo_u32 v0, s80, v15
	v_mul_lo_u32 v11, s81, v14
	v_mad_u64_u32 v[16:17], s[42:43], s80, v14, 0
	v_add3_u32 v17, v17, v0, v11
	v_ashrrev_i32_e32 v11, 31, v10
	v_lshl_add_u64 v[16:17], v[16:17], 2, v[12:13]
	v_lshl_add_u64 v[16:17], v[10:11], 2, v[16:17]
	v_mov_b32_e32 v60, 1.0
	v_mov_b32_e32 v61, 1.0
	v_mov_b32_e32 v62, 1.0
	v_mov_b32_e32 v63, 1.0
	v_mov_b32_e32 v64, 1.0
	v_mov_b32_e32 v65, 1.0
	v_mov_b32_e32 v66, 1.0
	v_mov_b32_e32 v67, 1.0
	global_load_dword v0, v[16:17], off
	s_cmp_eq_u64 s[78:79], 0
	s_cbranch_scc1 .LBB0_96
	v_lshl_add_u64 v[14:15], v[14:15], 2, s[78:79]
	global_load_dword v60, v[14:15], off
.LBB0_96:
	v_add_u32_e32 v14, 0x200, v37
	v_ashrrev_i32_e32 v14, 6, v14
	v_add_u32_e32 v14, s74, v14
	v_ashrrev_i32_e32 v15, 31, v14
	v_mul_lo_u32 v18, s80, v15
	v_mul_lo_u32 v19, s81, v14
	v_mad_u64_u32 v[16:17], s[42:43], s80, v14, 0
	v_add3_u32 v17, v17, v18, v19
	v_lshl_add_u64 v[16:17], v[16:17], 2, v[12:13]
	v_lshl_add_u64 v[16:17], v[10:11], 2, v[16:17]
	global_load_dword v16, v[16:17], off
	v_cndmask_b32_e64 v17, 0, 1, s[86:87]
	v_cmp_ne_u32_e64 s[42:43], 1, v17
	s_andn2_b64 vcc, exec, s[86:87]
	s_cbranch_vccnz .LBB0_98
	v_lshl_add_u64 v[14:15], v[14:15], 2, s[78:79]
	global_load_dword v61, v[14:15], off
.LBB0_98:
	v_add_u32_e32 v14, 0x400, v37
	v_ashrrev_i32_e32 v14, 6, v14
	v_add_u32_e32 v14, s74, v14
	v_ashrrev_i32_e32 v15, 31, v14
	v_mul_lo_u32 v17, s80, v15
	v_mul_lo_u32 v20, s81, v14
	v_mad_u64_u32 v[18:19], s[56:57], s80, v14, 0
	v_add3_u32 v19, v19, v17, v20
	v_lshl_add_u64 v[18:19], v[18:19], 2, v[12:13]
	v_lshl_add_u64 v[18:19], v[10:11], 2, v[18:19]
	global_load_dword v17, v[18:19], off
	s_and_b64 vcc, exec, s[42:43]
	s_cbranch_vccnz .LBB0_100
	v_lshl_add_u64 v[14:15], v[14:15], 2, s[78:79]
	global_load_dword v62, v[14:15], off
.LBB0_100:
	v_add_u32_e32 v14, 0x600, v37
	v_ashrrev_i32_e32 v14, 6, v14
	v_add_u32_e32 v14, s74, v14
	v_ashrrev_i32_e32 v15, 31, v14
	v_mul_lo_u32 v20, s80, v15
	v_mul_lo_u32 v21, s81, v14
	v_mad_u64_u32 v[18:19], s[56:57], s80, v14, 0
	v_add3_u32 v19, v19, v20, v21
	v_lshl_add_u64 v[18:19], v[18:19], 2, v[12:13]
	v_lshl_add_u64 v[18:19], v[10:11], 2, v[18:19]
	global_load_dword v18, v[18:19], off
	s_and_b64 vcc, exec, s[42:43]
	s_cbranch_vccnz .LBB0_102
	v_lshl_add_u64 v[14:15], v[14:15], 2, s[78:79]
	global_load_dword v63, v[14:15], off
.LBB0_102:
	v_add_u32_e32 v14, 0x800, v37
	v_ashrrev_i32_e32 v14, 6, v14
	v_add_u32_e32 v14, s74, v14
	v_ashrrev_i32_e32 v15, 31, v14
	v_mul_lo_u32 v19, s80, v15
	v_mul_lo_u32 v22, s81, v14
	v_mad_u64_u32 v[20:21], s[56:57], s80, v14, 0
	v_add3_u32 v21, v21, v19, v22
	v_lshl_add_u64 v[20:21], v[20:21], 2, v[12:13]
	v_lshl_add_u64 v[20:21], v[10:11], 2, v[20:21]
	global_load_dword v19, v[20:21], off
	s_and_b64 vcc, exec, s[42:43]
	s_cbranch_vccnz .LBB0_104
	v_lshl_add_u64 v[14:15], v[14:15], 2, s[78:79]
	global_load_dword v64, v[14:15], off
.LBB0_104:
	v_add_u32_e32 v14, 0xa00, v37
	v_ashrrev_i32_e32 v14, 6, v14
	v_add_u32_e32 v14, s74, v14
	v_ashrrev_i32_e32 v15, 31, v14
	v_mul_lo_u32 v22, s80, v15
	v_mul_lo_u32 v23, s81, v14
	v_mad_u64_u32 v[20:21], s[56:57], s80, v14, 0
	v_add3_u32 v21, v21, v22, v23
	v_lshl_add_u64 v[20:21], v[20:21], 2, v[12:13]
	v_lshl_add_u64 v[20:21], v[10:11], 2, v[20:21]
	global_load_dword v20, v[20:21], off
	s_and_b64 vcc, exec, s[42:43]
	s_cbranch_vccnz .LBB0_106
	v_lshl_add_u64 v[14:15], v[14:15], 2, s[78:79]
	global_load_dword v65, v[14:15], off
.LBB0_106:
	v_add_u32_e32 v14, 0xc00, v37
	v_ashrrev_i32_e32 v14, 6, v14
	v_add_u32_e32 v14, s74, v14
	v_ashrrev_i32_e32 v15, 31, v14
	v_mul_lo_u32 v21, s80, v15
	v_mul_lo_u32 v24, s81, v14
	v_mad_u64_u32 v[22:23], s[56:57], s80, v14, 0
	v_add3_u32 v23, v23, v21, v24
	v_lshl_add_u64 v[22:23], v[22:23], 2, v[12:13]
	v_lshl_add_u64 v[22:23], v[10:11], 2, v[22:23]
	global_load_dword v21, v[22:23], off
	s_and_b64 vcc, exec, s[42:43]
	s_cbranch_vccnz .LBB0_108
	v_lshl_add_u64 v[14:15], v[14:15], 2, s[78:79]
	global_load_dword v66, v[14:15], off
.LBB0_108:
	v_add_u32_e32 v14, 0xe00, v37
	v_ashrrev_i32_e32 v14, 6, v14
	v_add_u32_e32 v14, s74, v14
	v_ashrrev_i32_e32 v15, 31, v14
	v_mul_lo_u32 v24, s80, v15
	v_mul_lo_u32 v25, s81, v14
	v_mad_u64_u32 v[22:23], s[56:57], s80, v14, 0
	v_add3_u32 v23, v23, v24, v25
	v_lshl_add_u64 v[12:13], v[22:23], 2, v[12:13]
	v_lshl_add_u64 v[10:11], v[10:11], 2, v[12:13]
	global_load_dword v75, v[10:11], off
	s_and_b64 vcc, exec, s[42:43]
	s_cbranch_vccnz .LBB0_110
	v_lshl_add_u64 v[10:11], v[14:15], 2, s[78:79]
	global_load_dword v67, v[10:11], off
.LBB0_110:
	s_waitcnt vmcnt(0)
	v_mul_f32_e32 v0, s2, v0
	v_mul_f32_e32 v16, s2, v16
	v_mul_f32_e32 v17, s2, v17
	v_mul_f32_e32 v18, s2, v18
	v_mul_f32_e32 v19, s2, v19
	v_mul_f32_e32 v20, s2, v20
	v_mul_f32_e32 v21, s2, v21
	v_mul_f32_e32 v22, s2, v75
	v_mul_f32_e32 v0, v0, v60
	v_mul_f32_e32 v16, v16, v61
	v_mul_f32_e32 v17, v17, v62
	v_mul_f32_e32 v18, v18, v63
	v_mul_f32_e32 v19, v19, v64
	v_mul_f32_e32 v20, v20, v65
	v_mul_f32_e32 v21, v21, v66
	v_mul_f32_e32 v22, v22, v67
	s_or_b64 s[0:1], s[38:39], s[0:1]
	s_or_b64 vcc, s[0:1], s[40:41]
	v_cndmask_b32_e32 v10, 0, v21, vcc
	v_cndmask_b32_e32 v11, 0, v20, vcc
	v_cndmask_b32_e32 v12, 0, v19, vcc
	v_cndmask_b32_e32 v13, 0, v18, vcc
	v_cndmask_b32_e32 v14, 0, v17, vcc
	v_cndmask_b32_e32 v15, 0, v16, vcc
	v_cndmask_b32_e32 v39, 0, v0, vcc
	v_cndmask_b32_e32 v40, 0, v22, vcc

; __device__ __forceinline__ void prep_load(const KP& p, int job, int tid, float (&v)[8], PrepMeta& m) {
;     ...
;     float x = sp[(size_t)k * ldn + c] * cs;
;     if (sc) x *= sc[k];
;     v[it] = ok ? x : 0.f;
.LBB0_113:
	s_waitcnt vmcnt(0)
	v_mul_f32_e32 v39, s47, v39
	v_mul_f32_e32 v40, s47, v40
	v_mul_f32_e32 v42, s47, v42
	v_mul_f32_e32 v43, s47, v43
	v_mul_f32_e32 v44, s47, v44
	v_mul_f32_e32 v45, s47, v45
	v_mul_f32_e32 v46, s47, v46
	v_mul_f32_e32 v47, s47, v75
	v_mul_f32_e32 v39, v39, v60
	v_mul_f32_e32 v40, v40, v61
	v_mul_f32_e32 v42, v42, v62
	v_mul_f32_e32 v43, v43, v63
	v_mul_f32_e32 v44, v44, v64
	v_mul_f32_e32 v45, v45, v65
	v_mul_f32_e32 v46, v46, v66
	v_mul_f32_e32 v47, v47, v67
	s_or_b64 s[0:1], s[40:41], s[0:1]
	s_or_b64 vcc, s[0:1], s[42:43]
	v_readlane_b32 s66, v255, 40
	s_mov_b32 s94, 0x1c000
	v_cndmask_b32_e32 v10, 0, v46, vcc
	v_cndmask_b32_e32 v11, 0, v45, vcc
	v_cndmask_b32_e32 v12, 0, v44, vcc
	v_cndmask_b32_e32 v13, 0, v43, vcc
	v_cndmask_b32_e32 v14, 0, v42, vcc
	v_cndmask_b32_e32 v15, 0, v40, vcc
	v_cndmask_b32_e32 v39, 0, v39, vcc
	v_cndmask_b32_e32 v40, 0, v47, vcc

; __device__ __forceinline__ void prep_load(const KP& p, int job, int tid, float (&v)[8], PrepMeta& m) {
;     ...
;   for (int it = 0; it < 8; ++it) {
;     int e = tid + 512 * it, kk = e >> 6, nn = e & 63;
;     int k = k0 + kk, n = n0 + nn, c; bool ok = true; const float* sp = s0;
;     const int nl = n & 255, bj = nl >> 7, wc_ = (nl >> 5) & 3, ns = (nl >> 4) & 1, r = nl & 15;
;     if (mat == 0) { c = (n >> 8) * 128 + wc_ * 32 + (r >> 2) * 8 + bj * 4 + (r & 3); if (ns) sp = s1; }
;     else {
;       c = (n & ~255) + bj * 128 + wc_ * 32 + (r >> 2) * 8 + ns * 4 + (r & 3);
;       if (mat == 2) { if (c < 1536) c = c; else if (c < 3584) c = c + 8; else if (c < 3592) c = 1536 + (c - 3584); else { ok = false; c = 0; } }
;     }
;     float x = sp[(size_t)k * ldn + c] * cs;
;     if (sc) x *= sc[k];
;     v[it] = ok ? x : 0.f;
;   }
.LBB0_136:
	s_lshl_b32 s61, s42, 6
	s_lshl_b32 s62, s62, 6
	s_bfe_u32 s43, s42, 0x10001
	v_or_b32_e32 v2, s61, v32
	s_cmp_lg_u64 s[84:85], 0
	v_bfe_u32 v2, v2, 5, 2
	s_cselect_b64 s[94:95], -1, 0
	s_and_b32 s0, s61, 0xffffff00
	s_lshl_b32 s1, s43, 7
	s_or_b32 s0, s1, s0
	v_lshlrev_b32_e32 v3, 5, v2
	v_or3_b32 v3, v3, s0, v33
	v_or_b32_e32 v4, v3, v34
	s_movk_i32 s0, 0x600
	s_cmpk_lt_u32 s61, 0xe00
	v_cmp_gt_i32_e32 vcc, s0, v4
	s_cselect_b64 s[0:1], -1, 0
	s_and_b32 s65, s42, 0x7fffffc
	s_movk_i32 s42, 0xe08
	v_or_b32_e32 v2, s65, v2
	v_mov_b32_e32 v6, s92
	v_mov_b32_e32 v7, s44
	s_lshl_b32 s66, s43, 2
	v_cmp_gt_u32_e64 s[42:43], s42, v3
	v_add_u32_e32 v3, 0xfffff800, v4
	v_lshlrev_b32_e32 v2, 5, v2
	v_cndmask_b32_e64 v8, v6, v7, s[38:39]
	v_mov_b32_e32 v6, s93
	v_mov_b32_e32 v9, s45
	s_or_b64 s[40:41], s[88:89], s[40:41]
	v_cndmask_b32_e64 v3, 0, v3, s[42:43]
	v_add_u32_e32 v5, 8, v4
	v_or3_b32 v2, v2, s66, v35
	v_cndmask_b32_e64 v41, v6, v9, s[38:39]
	v_add_u32_e32 v6, s62, v16
	s_or_b64 s[40:41], s[40:41], vcc
	v_cndmask_b32_e64 v2, v4, v2, s[88:89]
	v_cndmask_b32_e64 v3, v3, v5, s[0:1]
	v_cndmask_b32_e64 v4, v7, v8, s[88:89]
	v_ashrrev_i32_e32 v7, 31, v6
	v_cndmask_b32_e64 v2, v3, v2, s[40:41]
	v_cndmask_b32_e64 v5, v9, v41, s[88:89]
	v_mul_lo_u32 v3, s86, v7
	v_mul_lo_u32 v41, s87, v6
	v_mad_u64_u32 v[8:9], s[44:45], s86, v6, 0
	v_add3_u32 v9, v9, v3, v41
	v_ashrrev_i32_e32 v3, 31, v2
	v_lshl_add_u64 v[8:9], v[8:9], 2, v[4:5]
	v_lshl_add_u64 v[8:9], v[2:3], 2, v[8:9]
	v_mov_b32_e32 v60, 1.0
	v_mov_b32_e32 v61, 1.0
	v_mov_b32_e32 v62, 1.0
	v_mov_b32_e32 v63, 1.0
	v_mov_b32_e32 v64, 1.0
	v_mov_b32_e32 v65, 1.0
	v_mov_b32_e32 v66, 1.0
	v_mov_b32_e32 v67, 1.0
	global_load_dword v8, v[8:9], off
	s_cmp_eq_u64 s[84:85], 0
	s_cbranch_scc1 .LBB0_138
	v_lshl_add_u64 v[6:7], v[6:7], 2, s[84:85]
	global_load_dword v60, v[6:7], off
.LBB0_138:
	v_add_u32_e32 v6, s62, v18
	v_ashrrev_i32_e32 v7, 31, v6
	v_mul_lo_u32 v9, s86, v7
	v_mul_lo_u32 v41, s87, v6
	v_mad_u64_u32 v[42:43], s[44:45], s86, v6, 0
	v_add3_u32 v43, v43, v9, v41
	v_lshl_add_u64 v[42:43], v[42:43], 2, v[4:5]
	v_lshl_add_u64 v[42:43], v[2:3], 2, v[42:43]
	global_load_dword v9, v[42:43], off
	v_cndmask_b32_e64 v41, 0, 1, s[94:95]
	v_cmp_ne_u32_e64 s[44:45], 1, v41
	s_andn2_b64 vcc, exec, s[94:95]
	s_cbranch_vccnz .LBB0_140
	v_lshl_add_u64 v[6:7], v[6:7], 2, s[84:85]
	global_load_dword v61, v[6:7], off
.LBB0_140:
	v_add_u32_e32 v6, s62, v20
	v_ashrrev_i32_e32 v7, 31, v6
	v_mul_lo_u32 v41, s86, v7
	v_mul_lo_u32 v44, s87, v6
	v_mad_u64_u32 v[42:43], s[66:67], s86, v6, 0
	v_add3_u32 v43, v43, v41, v44
	v_lshl_add_u64 v[42:43], v[42:43], 2, v[4:5]
	v_lshl_add_u64 v[42:43], v[2:3], 2, v[42:43]
	global_load_dword v41, v[42:43], off
	s_and_b64 vcc, exec, s[44:45]
	s_cbranch_vccnz .LBB0_142
	v_lshl_add_u64 v[6:7], v[6:7], 2, s[84:85]
	global_load_dword v62, v[6:7], off
.LBB0_142:
	v_add_u32_e32 v6, s62, v22
	v_ashrrev_i32_e32 v7, 31, v6
	v_mul_lo_u32 v44, s86, v7
	v_mul_lo_u32 v45, s87, v6
	v_mad_u64_u32 v[42:43], s[66:67], s86, v6, 0
	v_add3_u32 v43, v43, v44, v45
	v_lshl_add_u64 v[42:43], v[42:43], 2, v[4:5]
	v_lshl_add_u64 v[42:43], v[2:3], 2, v[42:43]
	global_load_dword v42, v[42:43], off
	s_and_b64 vcc, exec, s[44:45]
	s_cbranch_vccnz .LBB0_144
	v_lshl_add_u64 v[6:7], v[6:7], 2, s[84:85]
	global_load_dword v63, v[6:7], off
.LBB0_144:
	v_add_u32_e32 v6, s62, v24
	v_ashrrev_i32_e32 v7, 31, v6
	v_mul_lo_u32 v43, s86, v7
	v_mul_lo_u32 v46, s87, v6
	v_mad_u64_u32 v[44:45], s[66:67], s86, v6, 0
	v_add3_u32 v45, v45, v43, v46
	v_lshl_add_u64 v[44:45], v[44:45], 2, v[4:5]
	v_lshl_add_u64 v[44:45], v[2:3], 2, v[44:45]
	global_load_dword v43, v[44:45], off
	s_and_b64 vcc, exec, s[44:45]
	s_cbranch_vccnz .LBB0_146
	v_lshl_add_u64 v[6:7], v[6:7], 2, s[84:85]
	global_load_dword v64, v[6:7], off
.LBB0_146:
	v_add_u32_e32 v6, s62, v26
	v_ashrrev_i32_e32 v7, 31, v6
	v_mul_lo_u32 v46, s86, v7
	v_mul_lo_u32 v47, s87, v6
	v_mad_u64_u32 v[44:45], s[66:67], s86, v6, 0
	v_add3_u32 v45, v45, v46, v47
	v_lshl_add_u64 v[44:45], v[44:45], 2, v[4:5]
	v_lshl_add_u64 v[44:45], v[2:3], 2, v[44:45]
	global_load_dword v44, v[44:45], off
	s_and_b64 vcc, exec, s[44:45]
	s_cbranch_vccnz .LBB0_148
	v_lshl_add_u64 v[6:7], v[6:7], 2, s[84:85]
	global_load_dword v65, v[6:7], off
.LBB0_148:
	v_add_u32_e32 v6, s62, v28
	v_ashrrev_i32_e32 v7, 31, v6
	v_mul_lo_u32 v45, s86, v7
	v_mul_lo_u32 v48, s87, v6
	v_mad_u64_u32 v[46:47], s[66:67], s86, v6, 0
	v_add3_u32 v47, v47, v45, v48
	v_lshl_add_u64 v[46:47], v[46:47], 2, v[4:5]
	v_lshl_add_u64 v[46:47], v[2:3], 2, v[46:47]
	global_load_dword v45, v[46:47], off
	s_and_b64 vcc, exec, s[44:45]
	s_cbranch_vccnz .LBB0_150
	v_lshl_add_u64 v[6:7], v[6:7], 2, s[84:85]
	global_load_dword v66, v[6:7], off
.LBB0_150:
	v_add_u32_e32 v6, s62, v30
	v_ashrrev_i32_e32 v7, 31, v6
	v_mul_lo_u32 v48, s86, v7
	v_mul_lo_u32 v49, s87, v6
	v_mad_u64_u32 v[46:47], s[66:67], s86, v6, 0
	v_add3_u32 v47, v47, v48, v49
	v_lshl_add_u64 v[4:5], v[46:47], 2, v[4:5]
	v_lshl_add_u64 v[2:3], v[2:3], 2, v[4:5]
	global_load_dword v75, v[2:3], off
	s_and_b64 vcc, exec, s[44:45]
	s_cbranch_vccnz .LBB0_152
	v_lshl_add_u64 v[2:3], v[6:7], 2, s[84:85]
	global_load_dword v67, v[2:3], off
.LBB0_152:
	s_waitcnt vmcnt(0)
	v_mul_f32_e32 v8, s64, v8
	v_mul_f32_e32 v9, s64, v9
	v_mul_f32_e32 v41, s64, v41
	v_mul_f32_e32 v42, s64, v42
	v_mul_f32_e32 v43, s64, v43
	v_mul_f32_e32 v44, s64, v44
	v_mul_f32_e32 v45, s64, v45
	v_mul_f32_e32 v46, s64, v75
	v_mul_f32_e32 v8, v8, v60
	v_mul_f32_e32 v9, v9, v61
	v_mul_f32_e32 v41, v41, v62
	v_mul_f32_e32 v42, v42, v63
	v_mul_f32_e32 v43, v43, v64
	v_mul_f32_e32 v44, v44, v65
	v_mul_f32_e32 v45, v45, v66
	v_mul_f32_e32 v46, v46, v67
	s_or_b64 s[0:1], s[40:41], s[0:1]
	s_or_b64 vcc, s[0:1], s[42:43]
	v_readlane_b32 s66, v255, 40
	s_mov_b32 s94, 0x1c000
	v_cndmask_b32_e32 v2, 0, v8, vcc
	v_cndmask_b32_e32 v3, 0, v9, vcc
	v_cndmask_b32_e32 v4, 0, v41, vcc
	v_cndmask_b32_e32 v5, 0, v42, vcc
	v_cndmask_b32_e32 v6, 0, v43, vcc
	v_cndmask_b32_e32 v7, 0, v44, vcc
	v_cndmask_b32_e32 v8, 0, v45, vcc
	v_cndmask_b32_e32 v9, 0, v46, vcc

; __device__ __forceinline__ void prep_load(const KP& p, int job, int tid, float (&v)[8], PrepMeta& m) {
;     ...
;   for (int it = 0; it < 8; ++it) {
;     int e = tid + 512 * it, kk = e >> 6, nn = e & 63;
;     int k = k0 + kk, n = n0 + nn, c; bool ok = true; const float* sp = s0;
;     const int nl = n & 255, bj = nl >> 7, wc_ = (nl >> 5) & 3, ns = (nl >> 4) & 1, r = nl & 15;
;     if (mat == 0) { c = (n >> 8) * 128 + wc_ * 32 + (r >> 2) * 8 + bj * 4 + (r & 3); if (ns) sp = s1; }
;     else {
;       c = (n & ~255) + bj * 128 + wc_ * 32 + (r >> 2) * 8 + ns * 4 + (r & 3);
;       if (mat == 2) { if (c < 1536) c = c; else if (c < 3584) c = c + 8; else if (c < 3592) c = 1536 + (c - 3584); else { ok = false; c = 0; } }
;     }
;     float x = sp[(size_t)k * ldn + c] * cs;
.LBB0_174:
	s_lshl_b32 s65, s42, 6
	s_lshl_b32 s64, s64, 6
	s_bfe_u32 s43, s42, 0x10001
	v_or_b32_e32 v10, s65, v32
	s_cmp_lg_u64 s[76:77], 0
	v_bfe_u32 v10, v10, 5, 2
	s_cselect_b64 s[92:93], -1, 0
	s_and_b32 s0, s65, 0xffffff00
	s_lshl_b32 s1, s43, 7
	s_or_b32 s0, s1, s0
	v_lshlrev_b32_e32 v11, 5, v10
	v_or3_b32 v11, v11, s0, v33
	v_or_b32_e32 v12, v11, v34
	s_movk_i32 s0, 0x600
	s_cmpk_lt_u32 s65, 0xe00
	v_cmp_gt_i32_e32 vcc, s0, v12
	s_cselect_b64 s[0:1], -1, 0
	s_and_b32 s66, s42, 0x7fffffc
	s_movk_i32 s42, 0xe08
	v_or_b32_e32 v10, s66, v10
	v_mov_b32_e32 v14, s88
	v_mov_b32_e32 v15, s44
	s_lshl_b32 s67, s43, 2
	v_cmp_gt_u32_e64 s[42:43], s42, v11
	v_add_u32_e32 v11, 0xfffff800, v12
	v_lshlrev_b32_e32 v10, 5, v10
	v_cndmask_b32_e64 v39, v14, v15, s[38:39]
	v_mov_b32_e32 v14, s89
	v_mov_b32_e32 v40, s45
	s_or_b64 s[40:41], s[86:87], s[40:41]
	v_cndmask_b32_e64 v11, 0, v11, s[42:43]
	v_add_u32_e32 v13, 8, v12
	v_or3_b32 v10, v10, s67, v35
	v_cndmask_b32_e64 v42, v14, v40, s[38:39]
	v_add_u32_e32 v14, s64, v16
	s_or_b64 s[40:41], s[40:41], vcc
	v_cndmask_b32_e64 v10, v12, v10, s[86:87]
	v_cndmask_b32_e64 v11, v11, v13, s[0:1]
	v_cndmask_b32_e64 v12, v15, v39, s[86:87]
	v_ashrrev_i32_e32 v15, 31, v14
	v_cndmask_b32_e64 v10, v11, v10, s[40:41]
	v_cndmask_b32_e64 v13, v40, v42, s[86:87]
	v_mul_lo_u32 v11, s84, v15
	v_mul_lo_u32 v39, s85, v14
	v_mad_u64_u32 v[42:43], s[44:45], s84, v14, 0
	v_add3_u32 v43, v43, v11, v39
	v_ashrrev_i32_e32 v11, 31, v10
	v_lshl_add_u64 v[42:43], v[42:43], 2, v[12:13]
	v_lshl_add_u64 v[42:43], v[10:11], 2, v[42:43]
	v_mov_b32_e32 v60, 1.0
	v_mov_b32_e32 v61, 1.0
	v_mov_b32_e32 v62, 1.0
	v_mov_b32_e32 v63, 1.0
	v_mov_b32_e32 v64, 1.0
	v_mov_b32_e32 v65, 1.0
	v_mov_b32_e32 v66, 1.0
	v_mov_b32_e32 v67, 1.0
	global_load_dword v39, v[42:43], off
	s_cmp_eq_u64 s[76:77], 0
	s_cbranch_scc1 .LBB0_176
	v_lshl_add_u64 v[14:15], v[14:15], 2, s[76:77]
	global_load_dword v60, v[14:15], off
.LBB0_176:
	v_add_u32_e32 v14, s64, v18
	v_ashrrev_i32_e32 v15, 31, v14
	v_mul_lo_u32 v40, s84, v15
	v_mul_lo_u32 v44, s85, v14
	v_mad_u64_u32 v[42:43], s[44:45], s84, v14, 0
	v_add3_u32 v43, v43, v40, v44
	v_lshl_add_u64 v[42:43], v[42:43], 2, v[12:13]
	v_lshl_add_u64 v[42:43], v[10:11], 2, v[42:43]
	global_load_dword v40, v[42:43], off
	v_cndmask_b32_e64 v42, 0, 1, s[92:93]
	v_cmp_ne_u32_e64 s[44:45], 1, v42
	s_andn2_b64 vcc, exec, s[92:93]
	s_cbranch_vccnz .LBB0_178
	v_lshl_add_u64 v[14:15], v[14:15], 2, s[76:77]
	global_load_dword v61, v[14:15], off
.LBB0_178:
	v_add_u32_e32 v14, s64, v20
	v_ashrrev_i32_e32 v15, 31, v14
	v_mul_lo_u32 v44, s84, v15
	v_mul_lo_u32 v45, s85, v14
	v_mad_u64_u32 v[42:43], s[66:67], s84, v14, 0
	v_add3_u32 v43, v43, v44, v45
	v_lshl_add_u64 v[42:43], v[42:43], 2, v[12:13]
	v_lshl_add_u64 v[42:43], v[10:11], 2, v[42:43]
	global_load_dword v42, v[42:43], off
	s_and_b64 vcc, exec, s[44:45]
	s_cbranch_vccnz .LBB0_180
	v_lshl_add_u64 v[14:15], v[14:15], 2, s[76:77]
	global_load_dword v62, v[14:15], off
.LBB0_180:
	v_add_u32_e32 v14, s64, v22
	v_ashrrev_i32_e32 v15, 31, v14
	v_mul_lo_u32 v43, s84, v15
	v_mul_lo_u32 v46, s85, v14
	v_mad_u64_u32 v[44:45], s[66:67], s84, v14, 0
	v_add3_u32 v45, v45, v43, v46
	v_lshl_add_u64 v[44:45], v[44:45], 2, v[12:13]
	v_lshl_add_u64 v[44:45], v[10:11], 2, v[44:45]
	global_load_dword v43, v[44:45], off
	s_and_b64 vcc, exec, s[44:45]
	s_cbranch_vccnz .LBB0_182
	v_lshl_add_u64 v[14:15], v[14:15], 2, s[76:77]
	global_load_dword v63, v[14:15], off
.LBB0_182:
	v_add_u32_e32 v14, s64, v24
	v_ashrrev_i32_e32 v15, 31, v14
	v_mul_lo_u32 v46, s84, v15
	v_mul_lo_u32 v47, s85, v14
	v_mad_u64_u32 v[44:45], s[66:67], s84, v14, 0
	v_add3_u32 v45, v45, v46, v47
	v_lshl_add_u64 v[44:45], v[44:45], 2, v[12:13]
	v_lshl_add_u64 v[44:45], v[10:11], 2, v[44:45]
	global_load_dword v44, v[44:45], off
	s_and_b64 vcc, exec, s[44:45]
	s_cbranch_vccnz .LBB0_184
	v_lshl_add_u64 v[14:15], v[14:15], 2, s[76:77]
	global_load_dword v64, v[14:15], off
.LBB0_184:
	v_add_u32_e32 v14, s64, v26
	v_ashrrev_i32_e32 v15, 31, v14
	v_mul_lo_u32 v45, s84, v15
	v_mul_lo_u32 v48, s85, v14
	v_mad_u64_u32 v[46:47], s[66:67], s84, v14, 0
	v_add3_u32 v47, v47, v45, v48
	v_lshl_add_u64 v[46:47], v[46:47], 2, v[12:13]
	v_lshl_add_u64 v[46:47], v[10:11], 2, v[46:47]
	global_load_dword v45, v[46:47], off
	s_and_b64 vcc, exec, s[44:45]
	s_cbranch_vccnz .LBB0_186
	v_lshl_add_u64 v[14:15], v[14:15], 2, s[76:77]
	global_load_dword v65, v[14:15], off
.LBB0_186:
	v_add_u32_e32 v14, s64, v28
	v_ashrrev_i32_e32 v15, 31, v14
	v_mul_lo_u32 v48, s84, v15
	v_mul_lo_u32 v49, s85, v14
	v_mad_u64_u32 v[46:47], s[66:67], s84, v14, 0
	v_add3_u32 v47, v47, v48, v49
	v_lshl_add_u64 v[46:47], v[46:47], 2, v[12:13]
	v_lshl_add_u64 v[46:47], v[10:11], 2, v[46:47]
	global_load_dword v46, v[46:47], off
	s_and_b64 vcc, exec, s[44:45]
	s_cbranch_vccnz .LBB0_188
	v_lshl_add_u64 v[14:15], v[14:15], 2, s[76:77]
	global_load_dword v66, v[14:15], off
.LBB0_188:
	v_add_u32_e32 v14, s64, v30
	v_ashrrev_i32_e32 v15, 31, v14
	v_mul_lo_u32 v47, s84, v15
	v_mul_lo_u32 v50, s85, v14
	v_mad_u64_u32 v[48:49], s[66:67], s84, v14, 0
	v_add3_u32 v49, v49, v47, v50
	v_lshl_add_u64 v[12:13], v[48:49], 2, v[12:13]
	v_lshl_add_u64 v[10:11], v[10:11], 2, v[12:13]
	global_load_dword v75, v[10:11], off
	s_and_b64 vcc, exec, s[44:45]
	s_cbranch_vccnz .LBB0_113
	v_lshl_add_u64 v[10:11], v[14:15], 2, s[76:77]
	global_load_dword v67, v[10:11], off
	s_branch .LBB0_113
